# inproj1 q/k epilogue: rope cos/sin prefetched in one batch for both tiles of a pair (first tile spills the parked accumulators to LDS during the rope section)
# baseline (speedup 1.0000x reference)
.LBB0_437:
	s_andn2_b64 vcc, exec, s[4:5]
	s_mov_b64 s[4:5], 0x1000
	s_cbranch_vccnz .LBB0_443
	s_cmp_lg_u32 s65, 0
	s_cbranch_scc0 .LBB0_447
	s_lshl_b64 s[58:59], s[0:1], 13
	s_cmp_eq_u32 s65, 1
	s_cselect_b64 s[56:57], -1, 0
	s_and_b64 s[0:1], s[56:57], exec
	s_cselect_b32 s1, s43, s45
	s_cselect_b32 s0, s42, s44
	v_mov_b32_e32 v120, v18
	v_mov_b32_e32 v121, v22
	v_mul_f32_e32 v122, v120, v120
	v_mul_f32_e32 v123, v121, v121
	global_load_dword v143, v192, s[0:1]
	global_load_dword v141, v192, s[0:1] offset:64
	global_load_dword v125, v192, s[0:1] offset:128
	global_load_dword v121, v192, s[0:1] offset:192
	global_load_dword v142, v192, s[0:1] offset:256
	global_load_dword v140, v192, s[0:1] offset:320
	v_and_b32_e32 v77, 64, v201
	v_xor_b32_e32 v76, 1, v201
	v_add_u32_e32 v77, 64, v77
	v_cmp_lt_i32_e32 vcc, v76, v77
	v_mov_b32_e32 v82, v41
	v_mov_b32_e32 v83, v45
	v_cndmask_b32_e32 v76, v201, v76, vcc
	v_lshlrev_b32_e32 v146, 2, v76
	v_xor_b32_e32 v76, 2, v201
	v_cmp_lt_i32_e32 vcc, v76, v77
	v_mul_f32_e32 v82, v82, v82
	v_mul_f32_e32 v83, v83, v83
	v_mul_f32_e32 v86, v36, v36
	v_mul_f32_e32 v87, v37, v37
	v_cndmask_b32_e32 v76, v201, v76, vcc
	v_lshlrev_b32_e32 v147, 2, v76
	v_xor_b32_e32 v76, 4, v201
	v_cmp_lt_i32_e32 vcc, v76, v77
	v_mov_b32_e32 v78, v48
	v_mov_b32_e32 v79, v52
	v_cndmask_b32_e32 v76, v201, v76, vcc
	v_lshlrev_b32_e32 v148, 2, v76
	v_xor_b32_e32 v76, 8, v201
	v_cmp_lt_i32_e32 vcc, v76, v77
	v_mov_b32_e32 v77, v44
	v_fma_f32 v86, v32, v32, v86
	v_fma_f32 v87, v33, v33, v87
	v_cndmask_b32_e32 v76, v201, v76, vcc
	v_lshlrev_b32_e32 v149, 2, v76
	v_mov_b32_e32 v76, v40
	v_mul_f32_e32 v76, v76, v76
	v_mul_f32_e32 v77, v77, v77
	v_mov_b32_e32 v88, v49
	v_mov_b32_e32 v89, v53
	v_mov_b32_e32 v126, v82
	v_mov_b32_e32 v127, v76
	v_mul_f32_e32 v78, v78, v78
	v_mul_f32_e32 v79, v79, v79
	v_mul_f32_e32 v88, v88, v88
	v_mul_f32_e32 v89, v89, v89
	v_pk_add_f32 v[86:87], v[86:87], v[126:127] op_sel:[1,0] op_sel_hi:[0,1]
	v_mov_b32_e32 v76, v83
	v_mov_b32_e32 v80, v56
	v_mov_b32_e32 v81, v60
	v_mov_b32_e32 v90, v57
	v_mov_b32_e32 v91, v61
	v_add_f32_e32 v76, v86, v76
	v_add_f32_e32 v77, v87, v77
	v_mov_b32_e32 v82, v88
	v_mov_b32_e32 v83, v78
	v_mul_f32_e32 v80, v80, v80
	v_mul_f32_e32 v81, v81, v81
	v_mul_f32_e32 v90, v90, v90
	v_mul_f32_e32 v91, v91, v91
	v_add_f32_e32 v76, v76, v82
	v_add_f32_e32 v77, v77, v83
	v_mov_b32_e32 v78, v89
	v_add_f32_e32 v76, v76, v78
	v_add_f32_e32 v77, v77, v79
	v_mov_b32_e32 v78, v90
	v_mov_b32_e32 v79, v80
	v_add_f32_e32 v76, v76, v78
	v_add_f32_e32 v77, v77, v79
	v_mov_b32_e32 v80, v91
	v_add_f32_e32 v76, v76, v80
	v_add_f32_e32 v77, v77, v81
	s_nop 1
	v_mov_b32_dpp v79, v77 quad_perm:[1,0,3,2] row_mask:0xf bank_mask:0xf
	v_mov_b32_dpp v78, v76 quad_perm:[1,0,3,2] row_mask:0xf bank_mask:0xf
	global_load_dword v124, v192, s[0:1] offset:384
	global_load_dword v120, v192, s[0:1] offset:448
	v_mov_b32_e32 v88, v3
	v_mov_b32_e32 v89, v11
	s_waitcnt lgkmcnt(0)
	v_add_f32_e32 v76, v76, v78
	v_add_f32_e32 v77, v77, v79
	s_nop 1
	v_mov_b32_dpp v79, v77 quad_perm:[2,3,0,1] row_mask:0xf bank_mask:0xf
	v_mov_b32_dpp v78, v76 quad_perm:[2,3,0,1] row_mask:0xf bank_mask:0xf
	v_mov_b32_e32 v92, v42
	v_mov_b32_e32 v93, v46
	v_mov_b32_e32 v98, v43
	v_mov_b32_e32 v99, v47
	s_waitcnt lgkmcnt(0)
	v_add_f32_e32 v76, v76, v78
	v_add_f32_e32 v77, v77, v79
	s_nop 1
	v_mov_b32_dpp v79, v77 row_half_mirror row_mask:0xf bank_mask:0xf
	v_mov_b32_dpp v78, v76 row_half_mirror row_mask:0xf bank_mask:0xf
	v_mul_f32_e32 v90, v88, v88
	v_mul_f32_e32 v91, v89, v89
	v_mov_b32_e32 v88, v27
	v_mov_b32_e32 v89, v31
	v_mul_f32_e32 v84, v38, v38
	v_mul_f32_e32 v85, v39, v39
	s_waitcnt lgkmcnt(0)
	v_add_f32_e32 v76, v76, v78
	v_add_f32_e32 v77, v77, v79
	s_nop 1
	v_mov_b32_dpp v79, v77 row_mirror row_mask:0xf bank_mask:0xf
	v_mov_b32_dpp v78, v76 row_mirror row_mask:0xf bank_mask:0xf
	v_mul_f32_e32 v92, v92, v92
	v_mul_f32_e32 v93, v93, v93
	v_mul_f32_e32 v98, v98, v98
	v_mul_f32_e32 v99, v99, v99
	v_fma_f32 v84, v34, v34, v84
	v_fma_f32 v85, v35, v35, v85
	v_mov_b32_e32 v94, v50
	s_waitcnt lgkmcnt(0)
	v_add_f32_e32 v76, v76, v78
	v_add_f32_e32 v77, v77, v79
	v_mov_b64_e32 v[78:79], s[52:53]
	v_fma_f32 v76, v76, s46, v78
	v_fma_f32 v77, v77, s46, v78
	v_mov_b32_e32 v95, v54
	v_mul_f32_e32 v126, 0x4b800000, v77
	v_cmp_gt_f32_e32 vcc, s60, v77
	v_cmp_gt_f32_e64 s[0:1], s60, v76
	v_mov_b32_e32 v100, v51
	v_cndmask_b32_e32 v77, v77, v126, vcc
	v_rsq_f32_e32 v126, v77
	v_mul_f32_e32 v77, 0x4b800000, v76
	v_cndmask_b32_e64 v76, v76, v77, s[0:1]
	v_rsq_f32_e32 v127, v76
	v_mul_f32_e32 v76, v88, v88
	v_mul_f32_e32 v77, v89, v89
	v_mul_f32_e32 v88, 0x45800000, v126
	v_mov_b32_e32 v101, v55
	v_cndmask_b32_e32 v126, v126, v88, vcc
	v_mov_b32_e32 v88, v98
	v_mov_b32_e32 v89, v92
	v_mul_f32_e32 v94, v94, v94
	v_mul_f32_e32 v95, v95, v95
	v_mul_f32_e32 v100, v100, v100
	v_mul_f32_e32 v101, v101, v101
	v_pk_add_f32 v[84:85], v[84:85], v[88:89] op_sel:[1,0] op_sel_hi:[0,1]
	v_mov_b32_e32 v92, v99
	v_mov_b32_e32 v96, v58
	v_mov_b32_e32 v97, v62
	v_mov_b32_e32 v102, v59
	v_mov_b32_e32 v103, v63
	v_add_f32_e32 v84, v84, v92
	v_add_f32_e32 v85, v85, v93
	v_mov_b32_e32 v88, v100
	v_mov_b32_e32 v89, v94
	v_mul_f32_e32 v96, v96, v96
	v_mul_f32_e32 v97, v97, v97
	v_mul_f32_e32 v102, v102, v102
	v_mul_f32_e32 v103, v103, v103
	v_add_f32_e32 v84, v84, v88
	v_add_f32_e32 v85, v85, v89
	v_mov_b32_e32 v94, v101
	v_add_f32_e32 v84, v84, v94
	v_add_f32_e32 v85, v85, v95
	v_mov_b32_e32 v88, v102
	v_mov_b32_e32 v89, v96
	v_add_f32_e32 v84, v84, v88
	v_add_f32_e32 v85, v85, v89
	v_mov_b32_e32 v96, v103
	v_add_f32_e32 v84, v84, v96
	v_add_f32_e32 v85, v85, v97
	s_nop 1
	v_mov_b32_dpp v89, v85 quad_perm:[1,0,3,2] row_mask:0xf bank_mask:0xf
	v_mov_b32_dpp v88, v84 quad_perm:[1,0,3,2] row_mask:0xf bank_mask:0xf
	v_mul_f32_e32 v144, 0x45800000, v127
	v_mov_b32_e32 v104, v16
	v_mov_b32_e32 v105, v20
	v_mov_b32_e32 v110, v17
	s_waitcnt lgkmcnt(0)
	v_add_f32_e32 v84, v84, v88
	v_add_f32_e32 v85, v85, v89
	s_nop 1
	v_mov_b32_dpp v89, v85 quad_perm:[2,3,0,1] row_mask:0xf bank_mask:0xf
	v_mov_b32_dpp v88, v84 quad_perm:[2,3,0,1] row_mask:0xf bank_mask:0xf
	v_mov_b32_e32 v111, v21
	v_cndmask_b32_e64 v96, v127, v144, s[0:1]
	v_mul_f32_e32 v104, v104, v104
	v_mul_f32_e32 v105, v105, v105
	v_mul_f32_e32 v110, v110, v110
	v_mul_f32_e32 v111, v111, v111
	v_mul_f32_e32 v114, v12, v12
	v_mul_f32_e32 v115, v13, v13
	s_waitcnt vmcnt(0)
	v_mul_f32_e32 v92, v96, v143
	v_mov_b32_e32 v106, v0
	v_mov_b32_e32 v107, v8
	v_fma_f32 v114, v4, v4, v114
	v_fma_f32 v115, v5, v5, v115
	v_mov_b32_e32 v116, v1
	v_mov_b32_e32 v117, v9
	v_mul_f32_e32 v127, v33, v92
	s_waitcnt lgkmcnt(0)
	v_add_f32_e32 v84, v84, v88
	v_add_f32_e32 v85, v85, v89
	v_mov_b32_e32 v92, v110
	v_mov_b32_e32 v93, v104
	v_mul_f32_e32 v106, v106, v106
	v_mul_f32_e32 v107, v107, v107
	v_mul_f32_e32 v116, v116, v116
	v_mul_f32_e32 v117, v117, v117
	v_mov_b32_dpp v89, v85 row_half_mirror row_mask:0xf bank_mask:0xf
	v_mov_b32_dpp v88, v84 row_half_mirror row_mask:0xf bank_mask:0xf
	v_add_f32_e32 v92, v115, v92
	v_add_f32_e32 v93, v114, v93
	v_mov_b32_e32 v104, v111
	v_mov_b32_e32 v108, v24
	v_mov_b32_e32 v109, v28
	v_mov_b32_e32 v118, v25
	v_mov_b32_e32 v119, v29
	v_add_f32_e32 v92, v92, v104
	v_add_f32_e32 v93, v93, v105
	v_mov_b32_e32 v94, v116
	v_mov_b32_e32 v95, v106
	v_mul_f32_e32 v108, v108, v108
	v_mul_f32_e32 v109, v109, v109
	v_mul_f32_e32 v118, v118, v118
	v_mul_f32_e32 v119, v119, v119
	v_add_f32_e32 v92, v92, v94
	v_add_f32_e32 v93, v93, v95
	v_mov_b32_e32 v106, v117
	v_add_f32_e32 v92, v92, v106
	v_add_f32_e32 v93, v93, v107
	v_mov_b32_e32 v94, v118
	v_mov_b32_e32 v95, v108
	v_add_f32_e32 v92, v92, v94
	v_add_f32_e32 v93, v93, v95
	v_mov_b32_e32 v108, v119
	s_waitcnt lgkmcnt(0)
	v_add_f32_e32 v84, v84, v88
	v_add_f32_e32 v85, v85, v89
	v_add_f32_e32 v92, v92, v108
	v_add_f32_e32 v93, v93, v109
	v_mov_b32_dpp v89, v85 row_mirror row_mask:0xf bank_mask:0xf
	v_mov_b32_dpp v88, v84 row_mirror row_mask:0xf bank_mask:0xf
	v_mov_b32_dpp v95, v93 quad_perm:[1,0,3,2] row_mask:0xf bank_mask:0xf
	v_mov_b32_dpp v94, v92 quad_perm:[1,0,3,2] row_mask:0xf bank_mask:0xf
	v_mul_f32_e32 v33, v96, v141
	v_mul_f32_e32 v150, v37, v33
	s_waitcnt lgkmcnt(2)
	v_add_f32_e32 v84, v84, v88
	v_add_f32_e32 v85, v85, v89
	v_mul_f32_e32 v33, v96, v125
	s_waitcnt lgkmcnt(0)
	v_add_f32_e32 v88, v92, v94
	v_add_f32_e32 v89, v93, v95
	s_nop 1
	v_mov_b32_dpp v93, v89 quad_perm:[2,3,0,1] row_mask:0xf bank_mask:0xf
	v_mov_b32_dpp v92, v88 quad_perm:[2,3,0,1] row_mask:0xf bank_mask:0xf
	v_fma_f32 v84, v84, s46, v78
	v_fma_f32 v85, v85, s46, v78
	v_mul_f32_e32 v151, v41, v33
	v_mul_f32_e32 v37, 0x4b800000, v85
	v_cmp_gt_f32_e32 vcc, s60, v85
	s_waitcnt lgkmcnt(0)
	v_add_f32_e32 v88, v88, v92
	v_add_f32_e32 v89, v89, v93
	s_nop 1
	v_mov_b32_dpp v93, v89 row_half_mirror row_mask:0xf bank_mask:0xf
	v_mov_b32_dpp v92, v88 row_half_mirror row_mask:0xf bank_mask:0xf
	v_mul_f32_e32 v41, 0x4b800000, v84
	v_cmp_gt_f32_e64 s[0:1], s60, v84
	v_cndmask_b32_e32 v37, v85, v37, vcc
	v_mul_f32_e32 v33, v96, v121
	s_waitcnt lgkmcnt(0)
	v_add_f32_e32 v88, v88, v92
	v_add_f32_e32 v89, v89, v93
	s_nop 1
	v_mov_b32_dpp v93, v89 row_mirror row_mask:0xf bank_mask:0xf
	v_mov_b32_dpp v92, v88 row_mirror row_mask:0xf bank_mask:0xf
	v_cndmask_b32_e64 v41, v84, v41, s[0:1]
	v_mul_f32_e32 v203, v45, v33
	v_mul_f32_e32 v33, v96, v142
	v_rsq_f32_e32 v37, v37
	s_waitcnt lgkmcnt(0)
	v_add_f32_e32 v84, v88, v92
	v_add_f32_e32 v85, v89, v93
	v_mul_f32_e32 v204, v49, v33
	v_fma_f32 v84, v84, s46, v78
	v_fma_f32 v85, v85, s46, v78
	v_mul_f32_e32 v33, v96, v140
	v_mul_f32_e32 v45, 0x4b800000, v85
	v_cmp_gt_f32_e64 s[4:5], s60, v85
	v_rsq_f32_e32 v41, v41
	v_mul_f32_e32 v104, v53, v33
	v_cndmask_b32_e64 v45, v85, v45, s[4:5]
	v_mul_f32_e32 v33, v96, v124
	v_rsq_f32_e32 v45, v45
	v_mul_f32_e32 v105, v57, v33
	v_mul_f32_e32 v33, v96, v120
	v_mul_f32_e32 v106, v61, v33
	v_mul_f32_e32 v33, 0x45800000, v37
	v_cndmask_b32_e32 v92, v37, v33, vcc
	v_mul_f32_e32 v33, 0x45800000, v41
	v_cndmask_b32_e64 v88, v41, v33, s[0:1]
	v_mul_f32_e32 v33, 0x45800000, v45
	v_cndmask_b32_e64 v108, v45, v33, s[4:5]
	v_mul_f32_e32 v33, 0x4b800000, v84
	v_cmp_gt_f32_e32 vcc, s60, v84
	v_mov_b32_e32 v86, v19
	v_mov_b32_e32 v87, v23
	v_cndmask_b32_e32 v33, v84, v33, vcc
	v_lshl_add_u64 v[84:85], s[58:59], 0, v[72:73]
	v_lshlrev_b64 v[144:145], 2, v[84:85]
	s_cmp_lg_u32 s89, 0
	s_cbranch_scc1 .Lmy_rp_nospill
	ds_write_b128 v129, v[188:191] offset:0
	ds_write_b128 v129, v[208:211] offset:4096
	ds_write_b128 v129, v[232:235] offset:8192
	ds_write_b128 v129, v[236:239] offset:12288
	ds_write_b128 v129, v[240:243] offset:16384
	ds_write_b128 v129, v[248:251] offset:20480
	ds_write_b128 v129, v[252:255] offset:24576
	ds_write_b32 v129, v66 offset:28672
	ds_write_b32 v129, v67 offset:28676
	ds_write_b32 v129, v68 offset:28680
	ds_write_b32 v129, v69 offset:28684
	ds_write_b32 v129, v71 offset:32768
	ds_write_b32 v129, v74 offset:32772
	ds_write_b32 v129, v75 offset:32776
	ds_write_b32 v129, v160 offset:32780
	ds_write_b32 v129, v161 offset:45056
	ds_write_b32 v129, v162 offset:45060
	ds_write_b32 v129, v185 offset:45064
	ds_write_b32 v129, v186 offset:45068
	ds_write_b32 v129, v187 offset:49152
	ds_write_b32 v129, v207 offset:49156
	ds_write_b32 v129, v212 offset:49160
	ds_write_b32 v129, v213 offset:49164
	ds_write_b32 v129, v214 offset:53248
	ds_write_b32 v129, v216 offset:53252
	ds_write_b32 v129, v218 offset:53256
	ds_write_b32 v129, v220 offset:53260
	ds_write_b32 v129, v222 offset:57344
	ds_write_b32 v129, v224 offset:57348
	ds_write_b32 v129, v226 offset:57352
	ds_write_b32 v129, v228 offset:57356
	ds_write_b32 v129, v230 offset:61440
	ds_write_b32 v129, v231 offset:61444
	ds_write_b32 v129, v244 offset:61448
	ds_write_b32 v129, v245 offset:61452
	s_waitcnt lgkmcnt(0)
.Lmy_rp_nospill:
	s_add_u32 s10, s6, 0x1000
	s_addc_u32 s11, s7, 0
	s_add_u32 s12, s8, 0x1000
	s_addc_u32 s13, s9, 0
	global_load_dword v188, v144, s[6:7] offset:256
	global_load_dword v189, v144, s[8:9] offset:256
	global_load_dword v190, v144, s[6:7] offset:320
	global_load_dword v191, v144, s[8:9] offset:320
	global_load_dword v208, v144, s[6:7] offset:384
	global_load_dword v209, v144, s[8:9] offset:384
	global_load_dword v210, v144, s[6:7] offset:448
	global_load_dword v211, v144, s[8:9] offset:448
	global_load_dword v232, v144, s[6:7] offset:512
	global_load_dword v233, v144, s[8:9] offset:512
	global_load_dword v234, v144, s[6:7] offset:576
	global_load_dword v235, v144, s[8:9] offset:576
	global_load_dword v236, v144, s[6:7] offset:640
	global_load_dword v237, v144, s[8:9] offset:640
	global_load_dword v238, v144, s[6:7] offset:704
	global_load_dword v239, v144, s[8:9] offset:704
	global_load_dword v240, v144, s[6:7] offset:768
	global_load_dword v241, v144, s[8:9] offset:768
	global_load_dword v242, v144, s[6:7] offset:832
	global_load_dword v243, v144, s[8:9] offset:832
	global_load_dword v248, v144, s[6:7] offset:896
	global_load_dword v249, v144, s[8:9] offset:896
	global_load_dword v250, v144, s[6:7] offset:960
	global_load_dword v251, v144, s[8:9] offset:960
	global_load_dword v252, v144, s[10:11]
	global_load_dword v253, v144, s[12:13]
	global_load_dword v254, v144, s[10:11] offset:64
	global_load_dword v255, v144, s[12:13] offset:64
	global_load_dword v66, v144, s[10:11] offset:128
	global_load_dword v67, v144, s[12:13] offset:128
	global_load_dword v68, v144, s[10:11] offset:192
	global_load_dword v69, v144, s[12:13] offset:192
	global_load_dword v71, v144, s[10:11] offset:256
	global_load_dword v74, v144, s[12:13] offset:256
	global_load_dword v75, v144, s[10:11] offset:320
	global_load_dword v160, v144, s[12:13] offset:320
	global_load_dword v161, v144, s[10:11] offset:384
	global_load_dword v162, v144, s[12:13] offset:384
	global_load_dword v185, v144, s[10:11] offset:448
	global_load_dword v186, v144, s[12:13] offset:448
	global_load_dword v187, v144, s[10:11] offset:512
	global_load_dword v207, v144, s[12:13] offset:512
	global_load_dword v212, v144, s[10:11] offset:576
	global_load_dword v213, v144, s[12:13] offset:576
	global_load_dword v214, v144, s[10:11] offset:640
	global_load_dword v216, v144, s[12:13] offset:640
	global_load_dword v218, v144, s[10:11] offset:704
	global_load_dword v220, v144, s[12:13] offset:704
	global_load_dword v222, v144, s[10:11] offset:768
	global_load_dword v224, v144, s[12:13] offset:768
	global_load_dword v226, v144, s[10:11] offset:832
	global_load_dword v228, v144, s[12:13] offset:832
	global_load_dword v230, v144, s[10:11] offset:896
	global_load_dword v231, v144, s[12:13] offset:896
	global_load_dword v244, v144, s[10:11] offset:960
	global_load_dword v245, v144, s[12:13] offset:960
	v_lshl_add_u64 v[84:85], s[6:7], 0, v[144:145]
	v_lshl_add_u64 v[94:95], s[8:9], 0, v[144:145]
	global_load_dword v85, v[84:85], off
	s_nop 0
	global_load_dword v84, v[94:95], off
	v_or_b32_e32 v94, 64, v144
	v_mov_b32_e32 v95, v145
	v_lshl_add_u64 v[96:97], s[6:7], 0, v[94:95]
	v_lshl_add_u64 v[94:95], s[8:9], 0, v[94:95]
	global_load_dword v97, v[96:97], off
	s_nop 0
	global_load_dword v96, v[94:95], off
	v_or_b32_e32 v98, 0x80, v144
	v_mov_b32_e32 v99, v145
	v_lshl_add_u64 v[100:101], s[6:7], 0, v[98:99]
	v_lshl_add_u64 v[98:99], s[8:9], 0, v[98:99]
	global_load_dword v101, v[100:101], off
	s_nop 0
	global_load_dword v100, v[98:99], off
	v_or_b32_e32 v98, 0xc0, v144
	v_mov_b32_e32 v99, v145
	v_lshl_add_u64 v[102:103], s[6:7], 0, v[98:99]
	v_lshl_add_u64 v[98:99], s[8:9], 0, v[98:99]
	global_load_dword v103, v[102:103], off
	s_nop 0
	global_load_dword v102, v[98:99], off
	v_mul_f32_e32 v112, v14, v14
	v_mul_f32_e32 v113, v15, v15
	v_mul_f32_e32 v86, v86, v86
	v_mul_f32_e32 v87, v87, v87
	v_fma_f32 v112, v6, v6, v112
	v_fma_f32 v113, v7, v7, v113
	v_mov_b32_e32 v80, v2
	v_mov_b32_e32 v81, v10
	v_mov_b32_e32 v94, v86
	v_mov_b32_e32 v95, v122
	v_mul_f32_e32 v80, v80, v80
	v_mul_f32_e32 v81, v81, v81
	v_add_f32_e32 v94, v113, v94
	v_add_f32_e32 v95, v112, v95
	v_mov_b32_e32 v122, v87
	v_mov_b32_e32 v82, v26
	v_mov_b32_e32 v83, v30
	v_add_f32_e32 v86, v94, v122
	v_add_f32_e32 v87, v95, v123
	v_mov_b32_e32 v94, v90
	v_mov_b32_e32 v95, v80
	v_mul_f32_e32 v82, v82, v82
	v_mul_f32_e32 v83, v83, v83
	v_add_f32_e32 v86, v86, v94
	v_add_f32_e32 v87, v87, v95
	v_mov_b32_e32 v80, v91
	v_add_f32_e32 v80, v86, v80
	v_add_f32_e32 v81, v87, v81
	v_mov_b32_e32 v86, v76
	v_mov_b32_e32 v87, v82
	v_add_f32_e32 v80, v80, v86
	v_add_f32_e32 v81, v81, v87
	v_mov_b32_e32 v82, v77
	v_add_f32_e32 v76, v80, v82
	v_add_f32_e32 v77, v81, v83
	s_nop 1
	v_mov_b32_dpp v81, v77 quad_perm:[1,0,3,2] row_mask:0xf bank_mask:0xf
	v_mov_b32_dpp v80, v76 quad_perm:[1,0,3,2] row_mask:0xf bank_mask:0xf
	v_rsq_f32_e32 v33, v33
	v_mov_b32_e32 v49, v32
	v_mov_b32_e32 v53, v36
	v_mov_b32_e32 v57, v40
	s_waitcnt lgkmcnt(0)
	v_add_f32_e32 v76, v76, v80
	v_add_f32_e32 v77, v77, v81
	s_nop 1
	v_mov_b32_dpp v81, v77 quad_perm:[2,3,0,1] row_mask:0xf bank_mask:0xf
	v_mov_b32_dpp v80, v76 quad_perm:[2,3,0,1] row_mask:0xf bank_mask:0xf
	v_mul_f32_e32 v37, 0x45800000, v33
	v_cndmask_b32_e32 v33, v33, v37, vcc
	v_mul_f32_e32 v37, v33, v143
	v_mul_f32_e32 v41, v5, v37
	s_waitcnt lgkmcnt(0)
	v_add_f32_e32 v76, v76, v80
	v_add_f32_e32 v77, v77, v81
	s_nop 1
	v_mov_b32_dpp v81, v77 row_half_mirror row_mask:0xf bank_mask:0xf
	v_mov_b32_dpp v80, v76 row_half_mirror row_mask:0xf bank_mask:0xf
	v_mul_f32_e32 v5, v33, v141
	v_mul_f32_e32 v45, v13, v5
	v_mul_f32_e32 v5, v33, v125
	v_mul_f32_e32 v5, v17, v5
	s_waitcnt lgkmcnt(0)
	v_add_f32_e32 v76, v76, v80
	v_add_f32_e32 v77, v77, v81
	s_nop 1
	v_mov_b32_dpp v81, v77 row_mirror row_mask:0xf bank_mask:0xf
	v_mov_b32_dpp v80, v76 row_mirror row_mask:0xf bank_mask:0xf
	v_mul_f32_e32 v13, v33, v121
	v_mul_f32_e32 v17, v33, v142
	v_mul_f32_e32 v13, v21, v13
	v_mul_f32_e32 v21, v1, v17
	v_mul_f32_e32 v1, v33, v140
	s_waitcnt lgkmcnt(0)
	v_add_f32_e32 v76, v76, v80
	v_add_f32_e32 v77, v77, v81
	v_mul_f32_e32 v109, v9, v1
	v_mul_f32_e32 v1, v33, v124
	v_fma_f32 v76, v76, s46, v78
	v_fma_f32 v77, v77, s46, v78
	v_mul_f32_e32 v17, v25, v1
	v_mul_f32_e32 v9, 0x4b800000, v77
	v_cmp_gt_f32_e32 vcc, s60, v77
	v_mul_f32_e32 v25, 0x4b800000, v76
	v_cmp_gt_f32_e64 s[0:1], s60, v76
	v_cndmask_b32_e32 v9, v77, v9, vcc
	v_mul_f32_e32 v1, v33, v120
	v_cndmask_b32_e64 v25, v76, v25, s[0:1]
	v_mul_f32_e32 v76, v126, v142
	v_mul_f32_e32 v77, v126, v143
	v_mul_f32_e32 v32, v48, v76
	v_mul_f32_e32 v33, v49, v77
	s_waitcnt vmcnt(7)
	v_mov_b32_e32 v76, v85
	s_waitcnt vmcnt(6)
	v_mov_b32_e32 v77, v84
	v_rsq_f32_e32 v9, v9
	v_mul_f32_e32 v48, v32, v84
	v_mul_f32_e32 v49, v33, v85
	v_mul_f32_e32 v32, v32, v76
	v_mul_f32_e32 v33, v33, v77
	v_mul_f32_e32 v76, v126, v140
	v_mul_f32_e32 v77, v126, v141
	v_rsq_f32_e32 v25, v25
	v_mul_f32_e32 v36, v52, v76
	v_mul_f32_e32 v37, v53, v77
	s_waitcnt vmcnt(5)
	v_mov_b32_e32 v76, v97
	s_waitcnt vmcnt(4)
	v_mov_b32_e32 v77, v96
	v_mul_f32_e32 v52, v36, v96
	v_mul_f32_e32 v53, v37, v97
	v_mul_f32_e32 v36, v36, v76
	v_mul_f32_e32 v37, v37, v77
	v_mul_f32_e32 v76, v126, v124
	v_mul_f32_e32 v77, v126, v125
	v_mul_f32_e32 v56, v56, v76
	v_mul_f32_e32 v57, v57, v77
	s_waitcnt vmcnt(3)
	v_mov_b32_e32 v78, v101
	s_waitcnt vmcnt(2)
	v_mov_b32_e32 v79, v100
	v_mul_f32_e32 v110, v29, v1
	v_mul_f32_e32 v1, 0x45800000, v9
	v_mul_f32_e32 v76, v56, v100
	v_mul_f32_e32 v77, v57, v101
	v_mul_f32_e32 v56, v56, v78
	v_mul_f32_e32 v57, v57, v79
	v_mul_f32_e32 v78, v126, v120
	v_mul_f32_e32 v79, v126, v121
	v_mov_b32_e32 v61, v44
	v_cndmask_b32_e32 v148, v9, v1, vcc
	v_mul_f32_e32 v1, 0x45800000, v25
	v_mul_f32_e32 v60, v60, v78
	v_mul_f32_e32 v61, v61, v79
	v_cndmask_b32_e64 v146, v25, v1, s[0:1]
	s_waitcnt vmcnt(0)
	v_mul_f32_e32 v78, v60, v102
	v_mul_f32_e32 v79, v61, v103
	v_mov_b32_e32 v80, v103
	v_mov_b32_e32 v81, v102
	v_cndmask_b32_e64 v64, v202, 1.0, s[56:57]
	v_mul_f32_e32 v60, v60, v80
	v_mul_f32_e32 v61, v61, v81
	v_or_b32_e32 v80, 0x100, v144
	v_mov_b32_e32 v81, v145
	v_lshl_add_u64 v[82:83], s[6:7], 0, v[80:81]
	v_lshl_add_u64 v[80:81], s[8:9], 0, v[80:81]
	s_waitcnt vmcnt(0)
	v_mov_b32_e32 v1, v188
	v_mov_b32_e32 v9, v189
	v_or_b32_e32 v80, 0x140, v144
	v_mov_b32_e32 v81, v145
	v_lshl_add_u64 v[82:83], s[6:7], 0, v[80:81]
	v_lshl_add_u64 v[80:81], s[8:9], 0, v[80:81]
	v_or_b32_e32 v84, 0x180, v144
	v_mov_b32_e32 v85, v145
	v_lshl_add_u64 v[86:87], s[6:7], 0, v[84:85]
	v_lshl_add_u64 v[84:85], s[8:9], 0, v[84:85]
	v_mov_b32_e32 v25, v190
	v_mov_b32_e32 v29, v191
	v_mov_b32_e32 v40, v208
	v_mov_b32_e32 v44, v209
	v_or_b32_e32 v80, 0x1c0, v144
	v_mov_b32_e32 v81, v145
	v_lshl_add_u64 v[82:83], s[6:7], 0, v[80:81]
	v_lshl_add_u64 v[80:81], s[8:9], 0, v[80:81]
	v_mov_b32_e32 v89, v210
	v_mov_b32_e32 v93, v211
	v_mov_b32_e32 v82, v33
	v_mov_b32_e32 v84, v37
	v_mov_b32_e32 v80, v49
	v_mov_b32_e32 v86, v53
	v_mov_b32_e32 v90, v77
	v_mov_b32_e32 v94, v57
	v_mov_b32_e32 v96, v79
	v_mov_b32_e32 v98, v61
	s_waitcnt vmcnt(7)
	v_mul_f32_e32 v33, v204, v1
	s_waitcnt vmcnt(6)
	v_mul_f32_e32 v83, v127, v9
	v_mul_f32_e32 v81, v127, v1
	v_mul_f32_e32 v49, v204, v9
	v_add_f32_e32 v32, v32, v82
	v_add_f32_e32 v33, v33, v83
	v_add_f32_e64 v48, v80, -v48
	v_add_f32_e64 v49, v81, -v49
	s_waitcnt vmcnt(5)
	v_mul_f32_e32 v37, v104, v25
	s_waitcnt vmcnt(4)
	v_mul_f32_e32 v85, v150, v29
	v_mul_f32_e32 v87, v150, v25
	v_mul_f32_e32 v53, v104, v29
	s_waitcnt vmcnt(3)
	v_mul_f32_e32 v91, v151, v40
	s_waitcnt vmcnt(2)
	v_mul_f32_e32 v77, v105, v44
	v_mul_f32_e32 v95, v151, v44
	v_mul_f32_e32 v57, v105, v40
	s_waitcnt vmcnt(1)
	v_mul_f32_e32 v97, v203, v89
	s_waitcnt vmcnt(0)
	v_mul_f32_e32 v79, v106, v93
	v_mul_f32_e32 v99, v203, v93
	v_mul_f32_e32 v61, v106, v89
	v_add_f32_e32 v36, v36, v84
	v_add_f32_e32 v37, v37, v85
	v_add_f32_e32 v56, v56, v94
	v_add_f32_e32 v57, v57, v95
	v_add_f32_e32 v60, v60, v98
	v_add_f32_e32 v61, v61, v99
	v_mul_f32_e32 v84, v64, v32
	v_mul_f32_e32 v85, v64, v33
	v_add_f32_e64 v32, v86, -v52
	v_add_f32_e64 v33, v87, -v53
	v_mul_f32_e32 v86, v64, v36
	v_mul_f32_e32 v87, v64, v37
	v_add_f32_e64 v36, v90, -v76
	v_add_f32_e64 v37, v91, -v77
	v_add_f32_e64 v52, v96, -v78
	v_add_f32_e64 v53, v97, -v79
	v_mul_f32_e32 v90, v64, v56
	v_mul_f32_e32 v91, v64, v57
	v_mul_f32_e32 v76, v64, v48
	v_mul_f32_e32 v77, v64, v49
	v_mul_f32_e32 v78, v64, v32
	v_mul_f32_e32 v79, v64, v33
	v_mul_f32_e32 v80, v64, v36
	v_mul_f32_e32 v81, v64, v37
	v_mul_f32_e32 v82, v64, v52
	v_mul_f32_e32 v83, v64, v53
	v_mul_f32_e32 v94, v64, v60
	v_mul_f32_e32 v95, v64, v61
	v_or_b32_e32 v32, 0x200, v144
	v_mov_b32_e32 v33, v145
	v_or_b32_e32 v48, 0x240, v144
	v_mov_b32_e32 v49, v145
	v_lshl_add_u64 v[36:37], s[6:7], 0, v[32:33]
	v_lshl_add_u64 v[32:33], s[8:9], 0, v[32:33]
	v_lshl_add_u64 v[52:53], s[6:7], 0, v[48:49]
	v_lshl_add_u64 v[48:49], s[8:9], 0, v[48:49]
	v_or_b32_e32 v56, 0x280, v144
	v_mov_b32_e32 v57, v145
	v_lshl_add_u64 v[60:61], s[6:7], 0, v[56:57]
	v_lshl_add_u64 v[56:57], s[8:9], 0, v[56:57]
	s_waitcnt vmcnt(0)
	v_mov_b32_e32 v37, v232
	s_nop 0
	v_mov_b32_e32 v36, v233
	s_nop 0
	v_mov_b32_e32 v33, v234
	v_mov_b32_e32 v32, v235
	s_nop 0
	v_mov_b32_e32 v49, v236
	v_mov_b32_e32 v48, v237
	v_or_b32_e32 v52, 0x2c0, v144
	v_mov_b32_e32 v53, v145
	v_lshl_add_u64 v[56:57], s[6:7], 0, v[52:53]
	v_lshl_add_u64 v[52:53], s[8:9], 0, v[52:53]
	v_mov_b32_e32 v57, v238
	s_nop 0
	v_mov_b32_e32 v56, v239
	v_mul_f32_e32 v52, v92, v142
	v_mul_f32_e32 v53, v92, v143
	v_mov_b32_e32 v60, v50
	v_mov_b32_e32 v61, v34
	v_mul_f32_e32 v96, v92, v140
	v_mul_f32_e32 v97, v92, v141
	v_mov_b32_e32 v98, v54
	v_mov_b32_e32 v99, v38
	v_mul_f32_e32 v100, v92, v124
	v_mul_f32_e32 v101, v92, v125
	v_mov_b32_e32 v102, v58
	v_mov_b32_e32 v103, v42
	v_mul_f32_e32 v93, v92, v121
	v_mul_f32_e32 v92, v92, v120
	v_mov_b32_e32 v104, v62
	v_mov_b32_e32 v105, v46
	v_mul_f32_e32 v52, v60, v52
	v_mul_f32_e32 v53, v61, v53
	v_mul_f32_e32 v60, v98, v96
	v_mul_f32_e32 v61, v99, v97
	v_mul_f32_e32 v96, v102, v100
	v_mul_f32_e32 v97, v103, v101
	v_mul_f32_e32 v92, v104, v92
	v_mul_f32_e32 v93, v105, v93
	s_waitcnt vmcnt(7)
	v_mov_b32_e32 v100, v37
	s_waitcnt vmcnt(6)
	v_mul_f32_e32 v98, v52, v36
	v_mul_f32_e32 v99, v53, v37
	v_mov_b32_e32 v101, v36
	s_waitcnt vmcnt(4)
	v_mul_f32_e32 v102, v60, v32
	v_mul_f32_e32 v103, v61, v33
	v_mov_b32_e32 v36, v33
	v_mov_b32_e32 v37, v32
	s_waitcnt vmcnt(2)
	v_mul_f32_e32 v104, v96, v48
	v_mul_f32_e32 v105, v97, v49
	v_mov_b32_e32 v32, v49
	v_mov_b32_e32 v33, v48
	s_waitcnt vmcnt(1)
	v_mov_b32_e32 v106, v57
	s_waitcnt vmcnt(0)
	v_mov_b32_e32 v107, v56
	v_mul_f32_e32 v106, v92, v106
	v_mul_f32_e32 v107, v93, v107
	v_mul_f32_e32 v48, v92, v56
	v_mul_f32_e32 v49, v93, v57
	v_mul_f32_e32 v52, v52, v100
	v_mul_f32_e32 v53, v53, v101
	v_mul_f32_e32 v56, v60, v36
	v_mul_f32_e32 v57, v61, v37
	v_mul_f32_e32 v60, v96, v32
	v_mul_f32_e32 v61, v97, v33
	v_or_b32_e32 v32, 0x300, v144
	v_mov_b32_e32 v33, v145
	v_or_b32_e32 v92, 0x340, v144
	v_mov_b32_e32 v93, v145
	v_lshl_add_u64 v[36:37], s[6:7], 0, v[32:33]
	v_lshl_add_u64 v[96:97], s[6:7], 0, v[92:93]
	v_lshl_add_u64 v[92:93], s[8:9], 0, v[92:93]
	v_or_b32_e32 v100, 0x380, v144
	v_mov_b32_e32 v101, v145
	v_lshl_add_u64 v[32:33], s[8:9], 0, v[32:33]
	v_lshl_add_u64 v[112:113], s[6:7], 0, v[100:101]
	v_lshl_add_u64 v[100:101], s[8:9], 0, v[100:101]
	s_waitcnt vmcnt(0)
	v_mov_b32_e32 v114, v240
	v_mov_b32_e32 v115, v241
	s_nop 0
	v_mov_b32_e32 v96, v242
	s_nop 0
	v_mov_b32_e32 v97, v243
	s_nop 0
	v_mov_b32_e32 v92, v248
	v_mov_b32_e32 v93, v249
	v_or_b32_e32 v32, 0x3c0, v144
	v_mov_b32_e32 v33, v145
	v_lshl_add_u64 v[36:37], s[6:7], 0, v[32:33]
	v_lshl_add_u64 v[32:33], s[8:9], 0, v[32:33]
	v_mov_b32_e32 v112, v250
	v_mov_b32_e32 v113, v251
	v_mov_b32_e32 v32, v143
	v_mov_b32_e32 v33, v142
	v_mov_b32_e32 v50, v35
	v_mov_b32_e32 v34, v141
	v_mov_b32_e32 v35, v140
	v_mov_b32_e32 v54, v39
	v_mov_b32_e32 v36, v125
	v_mov_b32_e32 v37, v124
	v_mov_b32_e32 v38, v121
	v_mov_b32_e32 v39, v120
	v_mul_f32_e32 v116, v88, v32
	v_mul_f32_e32 v117, v88, v33
	v_mov_b32_e32 v58, v43
	v_mov_b32_e32 v62, v47
	v_mul_f32_e32 v118, v88, v34
	v_mul_f32_e32 v119, v88, v35
	v_mul_f32_e32 v122, v88, v36
	v_mul_f32_e32 v123, v88, v37
	v_mul_f32_e32 v89, v88, v39
	v_mul_f32_e32 v88, v88, v38
	v_mul_f32_e32 v50, v50, v116
	v_mul_f32_e32 v51, v51, v117
	v_mul_f32_e32 v54, v54, v118
	v_mul_f32_e32 v55, v55, v119
	v_mul_f32_e32 v58, v58, v122
	v_mul_f32_e32 v59, v59, v123
	v_mul_f32_e32 v62, v62, v88
	v_mul_f32_e32 v63, v63, v89
	v_mov_b32_e32 v42, v52
	v_mov_b32_e32 v100, v60
	v_mov_b32_e32 v46, v56
	s_waitcnt vmcnt(7)
	v_mov_b32_e32 v117, v114
	s_waitcnt vmcnt(6)
	v_mov_b32_e32 v116, v115
	v_mul_f32_e32 v88, v50, v114
	v_mul_f32_e32 v89, v51, v115
	v_mul_f32_e32 v50, v50, v116
	v_mul_f32_e32 v51, v51, v117
	s_waitcnt vmcnt(3)
	v_mov_b32_e32 v123, v92
	s_waitcnt vmcnt(2)
	v_mov_b32_e32 v122, v93
	v_mul_f32_e32 v114, v54, v96
	v_mul_f32_e32 v115, v55, v97
	v_mov_b32_e32 v118, v97
	v_mov_b32_e32 v119, v96
	v_mul_f32_e32 v96, v58, v92
	v_mul_f32_e32 v97, v59, v93
	v_mul_f32_e32 v58, v58, v122
	v_mul_f32_e32 v59, v59, v123
	v_mov_b32_e32 v43, v51
	v_pk_mov_b32 v[50:51], v[52:53], v[50:51] op_sel:[1,0]
	v_mul_f32_e32 v54, v54, v118
	v_mul_f32_e32 v55, v55, v119
	v_mov_b32_e32 v101, v59
	v_pk_mov_b32 v[58:59], v[60:61], v[58:59] op_sel:[1,0]
	v_add_f32_e32 v42, v42, v50
	v_add_f32_e32 v43, v43, v51
	v_mov_b32_e32 v47, v55
	v_pk_mov_b32 v[54:55], v[56:57], v[54:55] op_sel:[1,0]
	v_add_f32_e32 v50, v100, v58
	v_add_f32_e32 v51, v101, v59
	v_mul_f32_e32 v100, v64, v42
	v_mul_f32_e32 v101, v64, v43
	s_waitcnt vmcnt(0)
	v_mov_b32_e32 v42, v113
	v_mov_b32_e32 v43, v112
	v_mul_f32_e32 v92, v62, v112
	v_mul_f32_e32 v93, v63, v113
	v_pk_mov_b32 v[126:127], v[98:99], v[88:89] op_sel:[1,0]
	v_mov_b32_e32 v99, v89
	v_pk_mov_b32 v[88:89], v[102:103], v[114:115] op_sel:[1,0]
	v_mov_b32_e32 v103, v115
	v_add_f32_e32 v46, v46, v54
	v_add_f32_e32 v47, v47, v55
	v_mul_f32_e32 v42, v62, v42
	v_mul_f32_e32 v43, v63, v43
	v_pk_mov_b32 v[114:115], v[104:105], v[96:97] op_sel:[1,0]
	v_mov_b32_e32 v105, v97
	v_pk_mov_b32 v[96:97], v[48:49], v[92:93] op_sel:[1,0]
	v_mov_b32_e32 v49, v93
	v_add_f32_e64 v52, v88, -v102
	v_add_f32_e64 v53, v89, -v103
	v_mul_f32_e32 v102, v64, v46
	v_mul_f32_e32 v103, v64, v47
	v_mov_b32_e32 v46, v106
	v_mov_b32_e32 v47, v43
	v_pk_mov_b32 v[42:43], v[106:107], v[42:43] op_sel:[1,0]
	v_add_f32_e64 v92, v126, -v98
	v_add_f32_e64 v93, v127, -v99
	v_add_f32_e64 v56, v114, -v104
	v_add_f32_e64 v57, v115, -v105
	v_add_f32_e64 v48, v96, -v48
	v_add_f32_e64 v49, v97, -v49
	v_add_f32_e32 v42, v46, v42
	v_add_f32_e32 v43, v47, v43
	v_mul_f32_e32 v88, v64, v92
	v_mul_f32_e32 v89, v64, v93
	v_mul_f32_e32 v92, v64, v52
	v_mul_f32_e32 v93, v64, v53
	v_mul_f32_e32 v96, v64, v56
	v_mul_f32_e32 v97, v64, v57
	v_mul_f32_e32 v104, v64, v50
	v_mul_f32_e32 v105, v64, v51
	v_mul_f32_e32 v98, v64, v48
	v_mul_f32_e32 v99, v64, v49
	v_mul_f32_e32 v106, v64, v42
	v_mul_f32_e32 v107, v64, v43
	v_or_b32_e32 v42, 0x1000, v144
	v_mov_b32_e32 v43, v145
	v_or_b32_e32 v48, 0x1040, v144
	v_mov_b32_e32 v49, v145
	v_lshl_add_u64 v[46:47], s[6:7], 0, v[42:43]
	v_lshl_add_u64 v[42:43], s[8:9], 0, v[42:43]
	v_lshl_add_u64 v[50:51], s[6:7], 0, v[48:49]
	v_lshl_add_u64 v[48:49], s[8:9], 0, v[48:49]
	v_or_b32_e32 v52, 0x1080, v144
	v_mov_b32_e32 v53, v145
	v_lshl_add_u64 v[54:55], s[6:7], 0, v[52:53]
	v_lshl_add_u64 v[52:53], s[8:9], 0, v[52:53]
	s_waitcnt vmcnt(0)
	v_mov_b32_e32 v47, v252
	s_nop 0
	v_mov_b32_e32 v46, v253
	s_nop 0
	v_mov_b32_e32 v43, v254
	v_mov_b32_e32 v42, v255
	s_nop 0
	v_mov_b32_e32 v49, v66
	v_mov_b32_e32 v48, v67
	v_or_b32_e32 v50, 0x10c0, v144
	v_mov_b32_e32 v51, v145
	v_lshl_add_u64 v[52:53], s[6:7], 0, v[50:51]
	v_lshl_add_u64 v[50:51], s[8:9], 0, v[50:51]
	v_mov_b32_e32 v53, v68
	s_nop 0
	v_mov_b32_e32 v52, v69
	v_mul_f32_e32 v50, v108, v142
	v_mul_f32_e32 v51, v108, v143
	v_mov_b32_e32 v1, v4
	v_mul_f32_e32 v54, v108, v140
	v_mul_f32_e32 v55, v108, v141
	v_mov_b32_e32 v9, v12
	v_mul_f32_e32 v56, v108, v124
	v_mul_f32_e32 v57, v108, v125
	v_mov_b32_e32 v25, v16
	v_mul_f32_e32 v58, v108, v120
	v_mul_f32_e32 v59, v108, v121
	v_mov_b32_e32 v29, v20
	v_mul_f32_e32 v0, v0, v50
	v_mul_f32_e32 v1, v1, v51
	v_mul_f32_e32 v8, v8, v54
	v_mul_f32_e32 v9, v9, v55
	v_mul_f32_e32 v24, v24, v56
	v_mul_f32_e32 v25, v25, v57
	v_mul_f32_e32 v28, v28, v58
	v_mul_f32_e32 v29, v29, v59
	s_waitcnt vmcnt(7)
	v_mov_b32_e32 v54, v47
	s_waitcnt vmcnt(6)
	v_mov_b32_e32 v55, v46
	s_waitcnt vmcnt(5)
	v_mov_b32_e32 v56, v43
	s_waitcnt vmcnt(4)
	v_mov_b32_e32 v57, v42
	s_waitcnt vmcnt(3)
	v_mov_b32_e32 v58, v49
	s_waitcnt vmcnt(2)
	v_mov_b32_e32 v59, v48
	v_mul_f32_e32 v50, v0, v46
	v_mul_f32_e32 v51, v1, v47
	v_mul_f32_e32 v46, v8, v42
	v_mul_f32_e32 v47, v9, v43
	v_mul_f32_e32 v42, v24, v48
	v_mul_f32_e32 v43, v25, v49
	s_waitcnt vmcnt(1)
	v_mov_b32_e32 v60, v53
	s_waitcnt vmcnt(0)
	v_mov_b32_e32 v61, v52
	v_mul_f32_e32 v48, v28, v52
	v_mul_f32_e32 v49, v29, v53
	v_mul_f32_e32 v0, v0, v54
	v_mul_f32_e32 v1, v1, v55
	v_mul_f32_e32 v8, v8, v56
	v_mul_f32_e32 v9, v9, v57
	v_mul_f32_e32 v24, v24, v58
	v_mul_f32_e32 v25, v25, v59
	v_mul_f32_e32 v28, v28, v60
	v_mul_f32_e32 v29, v29, v61
	v_or_b32_e32 v52, 0x1100, v144
	v_mov_b32_e32 v53, v145
	v_lshl_add_u64 v[54:55], s[6:7], 0, v[52:53]
	v_lshl_add_u64 v[52:53], s[8:9], 0, v[52:53]
	s_waitcnt vmcnt(0)
	v_mov_b32_e32 v60, v71
	v_mov_b32_e32 v61, v74
	v_or_b32_e32 v52, 0x1140, v144
	v_mov_b32_e32 v53, v145
	v_or_b32_e32 v56, 0x1180, v144
	v_mov_b32_e32 v57, v145
	v_lshl_add_u64 v[54:55], s[6:7], 0, v[52:53]
	v_lshl_add_u64 v[52:53], s[8:9], 0, v[52:53]
	v_lshl_add_u64 v[58:59], s[6:7], 0, v[56:57]
	v_lshl_add_u64 v[56:57], s[8:9], 0, v[56:57]
	v_mov_b32_e32 v62, v75
	v_mov_b32_e32 v63, v160
	s_nop 0
	v_mov_b32_e32 v58, v161
	s_nop 0
	v_mov_b32_e32 v56, v162
	v_or_b32_e32 v52, 0x11c0, v144
	v_mov_b32_e32 v53, v145
	v_lshl_add_u64 v[54:55], s[6:7], 0, v[52:53]
	v_lshl_add_u64 v[52:53], s[8:9], 0, v[52:53]
	v_mov_b32_e32 v57, v185
	v_mov_b32_e32 v59, v186
	v_mov_b32_e32 v52, v51
	v_mov_b32_e32 v40, v1
	v_mov_b32_e32 v44, v9
	v_mov_b32_e32 v4, v25
	v_mov_b32_e32 v16, v49
	v_mov_b32_e32 v20, v47
	v_mov_b32_e32 v54, v43
	v_mov_b32_e32 v12, v29
	s_waitcnt vmcnt(7)
	v_mul_f32_e32 v53, v41, v60
	s_waitcnt vmcnt(6)
	v_mul_f32_e32 v51, v21, v61
	v_mul_f32_e32 v41, v41, v61
	v_mul_f32_e32 v1, v21, v60
	v_add_f32_e32 v0, v0, v40
	v_add_f32_e32 v1, v1, v41
	s_waitcnt vmcnt(5)
	v_mul_f32_e32 v21, v45, v62
	s_waitcnt vmcnt(4)
	v_mul_f32_e32 v45, v45, v63
	v_mul_f32_e32 v9, v109, v62
	s_waitcnt vmcnt(3)
	v_mul_f32_e32 v55, v5, v58
	s_waitcnt vmcnt(2)
	v_mul_f32_e32 v49, v17, v56
	v_mul_f32_e32 v5, v5, v56
	v_mul_f32_e32 v25, v17, v58
	v_mul_f32_e32 v47, v109, v63
	s_waitcnt vmcnt(0)
	v_mul_f32_e32 v56, v110, v59
	v_mul_f32_e32 v17, v13, v57
	v_mul_f32_e32 v13, v13, v59
	v_mul_f32_e32 v29, v110, v57
	v_add_f32_e32 v8, v8, v44
	v_add_f32_e32 v9, v9, v45
	v_mov_b32_e32 v43, v49
	v_add_f32_e32 v4, v24, v4
	v_add_f32_e32 v5, v25, v5
	v_mov_b32_e32 v49, v56
	v_add_f32_e32 v12, v28, v12
	v_add_f32_e32 v13, v29, v13
	v_add_f32_e64 v24, v52, -v50
	v_add_f32_e64 v25, v53, -v51
	v_mul_f32_e32 v116, v64, v0
	v_mul_f32_e32 v117, v64, v1
	v_add_f32_e64 v0, v20, -v46
	v_add_f32_e64 v1, v21, -v47
	v_mul_f32_e32 v118, v64, v8
	v_mul_f32_e32 v119, v64, v9
	v_add_f32_e64 v8, v54, -v42
	v_add_f32_e64 v9, v55, -v43
	v_mul_f32_e32 v122, v64, v4
	v_mul_f32_e32 v123, v64, v5
	v_add_f32_e64 v4, v16, -v48
	v_add_f32_e64 v5, v17, -v49
	v_mul_f32_e32 v108, v64, v24
	v_mul_f32_e32 v109, v64, v25
	v_mul_f32_e32 v110, v64, v0
	v_mul_f32_e32 v111, v64, v1
	v_mul_f32_e32 v112, v64, v8
	v_mul_f32_e32 v113, v64, v9
	v_mul_f32_e32 v114, v64, v4
	v_mul_f32_e32 v115, v64, v5
	v_mul_f32_e32 v126, v64, v12
	v_mul_f32_e32 v127, v64, v13
	v_or_b32_e32 v0, 0x1200, v144
	v_mov_b32_e32 v1, v145
	v_or_b32_e32 v8, 0x1240, v144
	v_mov_b32_e32 v9, v145
	v_lshl_add_u64 v[4:5], s[6:7], 0, v[0:1]
	v_lshl_add_u64 v[0:1], s[8:9], 0, v[0:1]
	v_lshl_add_u64 v[12:13], s[6:7], 0, v[8:9]
	v_lshl_add_u64 v[8:9], s[8:9], 0, v[8:9]
	v_or_b32_e32 v16, 0x1280, v144
	v_mov_b32_e32 v17, v145
	v_lshl_add_u64 v[20:21], s[6:7], 0, v[16:17]
	v_lshl_add_u64 v[16:17], s[8:9], 0, v[16:17]
	s_waitcnt vmcnt(0)
	v_mov_b32_e32 v5, v187
	s_nop 0
	v_mov_b32_e32 v4, v207
	s_nop 0
	v_mov_b32_e32 v1, v212
	v_mov_b32_e32 v0, v213
	s_nop 0
	v_mov_b32_e32 v9, v214
	v_mov_b32_e32 v8, v216
	v_or_b32_e32 v12, 0x12c0, v144
	v_mov_b32_e32 v13, v145
	v_lshl_add_u64 v[16:17], s[6:7], 0, v[12:13]
	v_lshl_add_u64 v[12:13], s[8:9], 0, v[12:13]
	v_mov_b32_e32 v17, v218
	s_nop 0
	v_mov_b32_e32 v16, v220
	v_mul_f32_e32 v12, v148, v142
	v_mul_f32_e32 v13, v148, v143
	v_mov_b32_e32 v20, v2
	v_mov_b32_e32 v21, v6
	v_mul_f32_e32 v24, v148, v140
	v_mul_f32_e32 v25, v148, v141
	v_mov_b32_e32 v28, v10
	v_mov_b32_e32 v29, v14
	v_mul_f32_e32 v40, v148, v124
	v_mul_f32_e32 v41, v148, v125
	v_mov_b32_e32 v42, v26
	v_mov_b32_e32 v43, v18
	v_mul_f32_e32 v44, v148, v120
	v_mul_f32_e32 v45, v148, v121
	v_mov_b32_e32 v46, v30
	v_mov_b32_e32 v47, v22
	v_mul_f32_e32 v12, v20, v12
	v_mul_f32_e32 v13, v21, v13
	v_mul_f32_e32 v20, v28, v24
	v_mul_f32_e32 v21, v29, v25
	v_mul_f32_e32 v24, v42, v40
	v_mul_f32_e32 v25, v43, v41
	v_mul_f32_e32 v28, v46, v44
	v_mul_f32_e32 v29, v47, v45
	s_waitcnt vmcnt(7)
	v_mov_b32_e32 v42, v5
	s_waitcnt vmcnt(6)
	v_mov_b32_e32 v43, v4
	s_waitcnt vmcnt(5)
	v_mov_b32_e32 v44, v1
	s_waitcnt vmcnt(4)
	v_mov_b32_e32 v45, v0
	s_waitcnt vmcnt(3)
	v_mov_b32_e32 v46, v9
	s_waitcnt vmcnt(2)
	v_mov_b32_e32 v47, v8
	v_mul_f32_e32 v40, v12, v4
	v_mul_f32_e32 v41, v13, v5
	v_mul_f32_e32 v4, v20, v0
	v_mul_f32_e32 v5, v21, v1
	v_mul_f32_e32 v0, v24, v8
	v_mul_f32_e32 v1, v25, v9
	s_waitcnt vmcnt(1)
	v_mov_b32_e32 v48, v17
	s_waitcnt vmcnt(0)
	v_mov_b32_e32 v49, v16
	v_mul_f32_e32 v8, v28, v16
	v_mul_f32_e32 v9, v29, v17
	v_mul_f32_e32 v12, v12, v42
	v_mul_f32_e32 v13, v13, v43
	v_mul_f32_e32 v16, v20, v44
	v_mul_f32_e32 v17, v21, v45
	v_mul_f32_e32 v20, v24, v46
	v_mul_f32_e32 v21, v25, v47
	v_mul_f32_e32 v24, v28, v48
	v_mul_f32_e32 v25, v29, v49
	v_or_b32_e32 v28, 0x1300, v144
	v_mov_b32_e32 v29, v145
	v_or_b32_e32 v44, 0x1340, v144
	v_mov_b32_e32 v45, v145
	v_lshl_add_u64 v[42:43], s[6:7], 0, v[28:29]
	v_lshl_add_u64 v[28:29], s[8:9], 0, v[28:29]
	v_lshl_add_u64 v[46:47], s[6:7], 0, v[44:45]
	v_lshl_add_u64 v[44:45], s[8:9], 0, v[44:45]
	v_or_b32_e32 v48, 0x1380, v144
	v_mov_b32_e32 v49, v145
	v_or_b32_e32 v144, 0x13c0, v144
	v_lshl_add_u64 v[50:51], s[6:7], 0, v[48:49]
	v_lshl_add_u64 v[48:49], s[8:9], 0, v[48:49]
	s_waitcnt vmcnt(0)
	v_mov_b32_e32 v42, v222
	s_nop 0
	v_mov_b32_e32 v43, v224
	s_nop 0
	v_mov_b32_e32 v28, v226
	v_mov_b32_e32 v29, v228
	s_nop 0
	v_mov_b32_e32 v44, v230
	v_mov_b32_e32 v45, v231
	v_lshl_add_u64 v[46:47], s[6:7], 0, v[144:145]
	v_lshl_add_u64 v[48:49], s[8:9], 0, v[144:145]
	v_mov_b32_e32 v46, v244
	s_nop 0
	v_mov_b32_e32 v47, v245
	s_cmp_lg_u32 s89, 0
	s_cbranch_scc1 .Lmy_rp_norest
	ds_read_b128 v[188:191], v129 offset:0
	ds_read_b128 v[208:211], v129 offset:4096
	ds_read_b128 v[232:235], v129 offset:8192
	ds_read_b128 v[236:239], v129 offset:12288
	ds_read_b128 v[240:243], v129 offset:16384
	ds_read_b128 v[248:251], v129 offset:20480
	ds_read_b128 v[252:255], v129 offset:24576
	ds_read_b32 v66, v129 offset:28672
	ds_read_b32 v67, v129 offset:28676
	ds_read_b32 v68, v129 offset:28680
	ds_read_b32 v69, v129 offset:28684
	ds_read_b32 v71, v129 offset:32768
	ds_read_b32 v74, v129 offset:32772
	ds_read_b32 v75, v129 offset:32776
	ds_read_b32 v160, v129 offset:32780
	ds_read_b32 v161, v129 offset:45056
	ds_read_b32 v162, v129 offset:45060
	ds_read_b32 v185, v129 offset:45064
	ds_read_b32 v186, v129 offset:45068
	ds_read_b32 v187, v129 offset:49152
	ds_read_b32 v207, v129 offset:49156
	ds_read_b32 v212, v129 offset:49160
	ds_read_b32 v213, v129 offset:49164
	ds_read_b32 v214, v129 offset:53248
	ds_read_b32 v216, v129 offset:53252
	ds_read_b32 v218, v129 offset:53256
	ds_read_b32 v220, v129 offset:53260
	ds_read_b32 v222, v129 offset:57344
	ds_read_b32 v224, v129 offset:57348
	ds_read_b32 v226, v129 offset:57352
	ds_read_b32 v228, v129 offset:57356
	ds_read_b32 v230, v129 offset:61440
	ds_read_b32 v231, v129 offset:61444
	ds_read_b32 v244, v129 offset:61448
	ds_read_b32 v245, v129 offset:61452
	s_waitcnt lgkmcnt(0)
	s_barrier
